# scan compute loop: scalar half of the next-chunk address set-up moved into step 0's DPP gap, six VALU adds remain before the chunk barrier
# baseline (speedup 1.0000x reference)
.LBB0_1050:
	ds_read_b128 v[14:17], v0 offset:20480
	ds_read_b128 v[10:13], v0 offset:20496
	ds_read_b128 v[6:9], v0 offset:20512
	ds_read_b128 v[2:5], v0 offset:20528
	ds_read_b128 v[54:57], v89 offset:16384
	ds_read_b128 v[26:29], v89 offset:16640
	ds_read_b128 v[78:81], v89 offset:4096
	ds_read_b128 v[58:61], v89 offset:4352
	ds_read_b128 v[30:33], v89 offset:4608
	ds_read_b128 v[22:25], v90 offset:8704
	ds_read_b128 v[18:21], v89 offset:16896
	v_pk_mul_f32 v[66:67], v[74:75], v[108:109]
	s_waitcnt lgkmcnt(4)
	v_pk_mul_f32 v[78:79], v[14:15], v[78:79] op_sel_hi:[0,1]
	v_pk_fma_f32 v[66:67], v[76:77], v[110:111], v[66:67]
	v_pk_mul_f32 v[80:81], v[14:15], v[80:81] op_sel_hi:[0,1]
	v_add_f32_e32 v66, v66, v67
	v_pk_fma_f32 v[62:63], v[74:75], v[100:101], v[78:79]
	v_pk_fma_f32 v[64:65], v[76:77], v[102:103], v[80:81]
	v_add_f32_dpp v66, v66, v66 quad_perm:[1,0,3,2] row_mask:0xf bank_mask:0xf bound_ctrl:1
	v_mov_b32_e32 v0, v17
	v_mov_b32_e32 v82, v13
	v_add_f32_dpp v66, v66, v66 quad_perm:[2,3,0,1] row_mask:0xf bank_mask:0xf bound_ctrl:1
	v_mov_b32_e32 v84, v9
	v_mov_b32_e32 v86, v5
	v_add_f32_dpp v66, v66, v66 row_half_mirror row_mask:0xf bank_mask:0xf bound_ctrl:1
	s_add_i32 s26, s26, 1
	s_and_b32 s2, s26, 1
	s_lshl_b32 s97, s2, 14
	s_mul_i32 s2, s2, 0x5400
	s_mov_b32 s3, s96
	s_add_i32 s96, s96, 0x3000
	s_cmp_eq_u32 s96, 0x1e800
	s_cselect_b32 s96, 0x20200, s96
	s_cmp_eq_u32 s96, 0x23200
	s_cselect_b32 s96, 0x12800, s96
	v_add_f32_dpp v66, v66, v66 row_ror:8 row_mask:0xf bank_mask:0xf bound_ctrl:1
	v_pk_fma_f32 v[62:63], v[120:121], v[66:67], v[62:63] op_sel_hi:[1,0,1] neg_lo:[1,0,0] neg_hi:[1,0,0]
	v_pk_fma_f32 v[64:65], v[122:123], v[66:67], v[64:65] op_sel_hi:[1,0,1] neg_lo:[1,0,0] neg_hi:[1,0,0]
	v_pk_mul_f32 v[50:51], v[112:113], v[62:63]
	v_pk_mul_f32 v[46:47], v[104:105], v[62:63]
	v_pk_fma_f32 v[50:51], v[114:115], v[64:65], v[50:51]
	s_waitcnt lgkmcnt(3)
	v_pk_fma_f32 v[66:67], v[14:15], v[58:59], v[46:47] op_sel:[1,0,0]
	v_add_f32_e32 v47, v50, v51
	v_pk_mul_f32 v[48:49], v[106:107], v[64:65]
	v_pk_mul_f32 v[56:57], v[56:57], v[64:65]
	v_add_f32_dpp v68, v47, v47 quad_perm:[1,0,3,2] row_mask:0xf bank_mask:0xf bound_ctrl:1
	v_pk_fma_f32 v[14:15], v[14:15], v[60:61], v[48:49] op_sel:[1,0,0]
	v_pk_fma_f32 v[54:55], v[54:55], v[62:63], v[56:57]
	v_add_f32_dpp v68, v68, v68 quad_perm:[2,3,0,1] row_mask:0xf bank_mask:0xf bound_ctrl:1
	v_add_f32_e32 v92, v54, v55
	s_nop 0
	v_add_f32_dpp v68, v68, v68 row_half_mirror row_mask:0xf bank_mask:0xf bound_ctrl:1
	ds_read_b128 v[46:49], v90 offset:768
	ds_read_b128 v[50:53], v89 offset:4864
	ds_read_b128 v[54:57], v90 offset:4864
	ds_read_b128 v[58:61], v90 offset:8960
	ds_read_b128 v[62:65], v89 offset:17152
	v_add_f32_dpp v68, v68, v68 row_ror:8 row_mask:0xf bank_mask:0xf bound_ctrl:1
	v_pk_fma_f32 v[42:43], v[128:129], v[68:69], v[66:67] op_sel_hi:[1,0,1] neg_lo:[1,0,0] neg_hi:[1,0,0]
	v_pk_fma_f32 v[14:15], v[130:131], v[68:69], v[14:15] op_sel_hi:[1,0,1] neg_lo:[1,0,0] neg_hi:[1,0,0]
	v_pk_mul_f32 v[38:39], v[124:125], v[42:43]
	v_pk_mul_f32 v[28:29], v[28:29], v[14:15]
	v_pk_mul_f32 v[36:37], v[118:119], v[14:15]
	v_pk_fma_f32 v[14:15], v[126:127], v[14:15], v[38:39]
	v_pk_mul_f32 v[34:35], v[116:117], v[42:43]
	v_add_f32_e32 v14, v14, v15
	v_pk_fma_f32 v[26:27], v[26:27], v[42:43], v[28:29]
	s_waitcnt lgkmcnt(7)
	v_pk_fma_f32 v[42:43], v[16:17], v[30:31], v[34:35] op_sel_hi:[0,1,1]
	v_add_f32_dpp v66, v14, v14 quad_perm:[1,0,3,2] row_mask:0xf bank_mask:0xf bound_ctrl:1
	v_pk_fma_f32 v[44:45], v[16:17], v[32:33], v[36:37] op_sel_hi:[0,1,1]
	v_add_f32_e32 v93, v26, v27
	v_add_f32_dpp v66, v66, v66 quad_perm:[2,3,0,1] row_mask:0xf bank_mask:0xf bound_ctrl:1
	ds_read_b128 v[14:17], v90 offset:1024
	ds_read_b128 v[26:29], v89 offset:5120
	ds_read_b128 v[30:33], v90 offset:5120
	ds_read_b128 v[34:37], v90 offset:9216
	ds_read_b128 v[38:41], v89 offset:17408
	v_add_f32_dpp v66, v66, v66 row_half_mirror row_mask:0xf bank_mask:0xf bound_ctrl:1
	s_nop 1
	v_add_f32_dpp v66, v66, v66 row_ror:8 row_mask:0xf bank_mask:0xf bound_ctrl:1
	s_waitcnt lgkmcnt(11)
	v_pk_fma_f32 v[22:23], v[22:23], v[66:67], v[42:43] op_sel_hi:[1,0,1] neg_lo:[1,0,0] neg_hi:[1,0,0]
	v_pk_fma_f32 v[24:25], v[24:25], v[66:67], v[44:45] op_sel_hi:[1,0,1] neg_lo:[1,0,0] neg_hi:[1,0,0]
	s_waitcnt lgkmcnt(7)
	v_pk_mul_f32 v[42:43], v[54:55], v[22:23]
	v_pk_mul_f32 v[20:21], v[20:21], v[24:25]
	v_pk_mul_f32 v[44:45], v[46:47], v[22:23]
	v_pk_mul_f32 v[46:47], v[48:49], v[24:25]
	v_pk_fma_f32 v[18:19], v[18:19], v[22:23], v[20:21]
	v_pk_fma_f32 v[20:21], v[56:57], v[24:25], v[42:43]
	v_pk_fma_f32 v[54:55], v[0:1], v[50:51], v[44:45] op_sel_hi:[0,1,1]
	v_pk_fma_f32 v[56:57], v[0:1], v[52:53], v[46:47] op_sel_hi:[0,1,1]
	v_add_f32_e32 v94, v18, v19
	v_add_f32_e32 v18, v20, v21
	s_nop 0
	s_nop 0
	v_add_f32_dpp v0, v18, v18 quad_perm:[1,0,3,2] row_mask:0xf bank_mask:0xf bound_ctrl:1
	ds_read_b128 v[18:21], v90 offset:1280
	ds_read_b128 v[22:25], v89 offset:5376
	v_add_f32_dpp v0, v0, v0 quad_perm:[2,3,0,1] row_mask:0xf bank_mask:0xf bound_ctrl:1
	ds_read_b128 v[42:45], v90 offset:5376
	ds_read_b128 v[46:49], v90 offset:9472
	v_add_f32_dpp v0, v0, v0 row_half_mirror row_mask:0xf bank_mask:0xf bound_ctrl:1
	ds_read_b128 v[50:53], v89 offset:17664
	s_nop 0
	v_add_f32_dpp v0, v0, v0 row_ror:8 row_mask:0xf bank_mask:0xf bound_ctrl:1
	s_waitcnt lgkmcnt(11)
	v_pk_fma_f32 v[54:55], v[58:59], v[0:1], v[54:55] op_sel_hi:[1,0,1] neg_lo:[1,0,0] neg_hi:[1,0,0]
	v_pk_fma_f32 v[56:57], v[60:61], v[0:1], v[56:57] op_sel_hi:[1,0,1] neg_lo:[1,0,0] neg_hi:[1,0,0]
	s_waitcnt lgkmcnt(7)
	v_pk_mul_f32 v[30:31], v[30:31], v[54:55]
	v_pk_mul_f32 v[58:59], v[64:65], v[56:57]
	v_pk_mul_f32 v[14:15], v[14:15], v[54:55]
	v_pk_fma_f32 v[54:55], v[62:63], v[54:55], v[58:59]
	v_pk_fma_f32 v[30:31], v[32:33], v[56:57], v[30:31]
	v_pk_fma_f32 v[62:63], v[10:11], v[26:27], v[14:15] op_sel_hi:[0,1,1]
	v_add_f32_e32 v95, v54, v55
	v_add_f32_e32 v14, v30, v31
	ds_write_b128 v91, v[92:95] offset:43008
	v_pk_mul_f32 v[16:17], v[16:17], v[56:57]
	v_add_f32_dpp v0, v14, v14 quad_perm:[1,0,3,2] row_mask:0xf bank_mask:0xf bound_ctrl:1
	v_pk_fma_f32 v[64:65], v[10:11], v[28:29], v[16:17] op_sel_hi:[0,1,1]
	ds_read_b128 v[14:17], v90 offset:1536
	v_add_f32_dpp v0, v0, v0 quad_perm:[2,3,0,1] row_mask:0xf bank_mask:0xf bound_ctrl:1
	ds_read_b128 v[26:29], v89 offset:5632
	ds_read_b128 v[30:33], v90 offset:5632
	v_add_f32_dpp v0, v0, v0 row_half_mirror row_mask:0xf bank_mask:0xf bound_ctrl:1
	ds_read_b128 v[54:57], v90 offset:9728
	ds_read_b128 v[58:61], v89 offset:17920
	v_add_f32_dpp v0, v0, v0 row_ror:8 row_mask:0xf bank_mask:0xf bound_ctrl:1
	s_waitcnt lgkmcnt(12)
	v_pk_fma_f32 v[34:35], v[34:35], v[0:1], v[62:63] op_sel_hi:[1,0,1] neg_lo:[1,0,0] neg_hi:[1,0,0]
	v_pk_fma_f32 v[36:37], v[36:37], v[0:1], v[64:65] op_sel_hi:[1,0,1] neg_lo:[1,0,0] neg_hi:[1,0,0]
	s_waitcnt lgkmcnt(8)
	v_pk_mul_f32 v[42:43], v[42:43], v[34:35]
	v_pk_mul_f32 v[40:41], v[40:41], v[36:37]
	v_pk_mul_f32 v[18:19], v[18:19], v[34:35]
	v_pk_mul_f32 v[20:21], v[20:21], v[36:37]
	v_pk_fma_f32 v[34:35], v[38:39], v[34:35], v[40:41]
	v_pk_fma_f32 v[36:37], v[44:45], v[36:37], v[42:43]
	v_pk_fma_f32 v[62:63], v[10:11], v[22:23], v[18:19] op_sel:[1,0,0]
	v_add_f32_e32 v18, v36, v37
	v_add_f32_e32 v96, v34, v35
	v_pk_fma_f32 v[10:11], v[10:11], v[24:25], v[20:21] op_sel:[1,0,0]
	v_add_f32_dpp v0, v18, v18 quad_perm:[1,0,3,2] row_mask:0xf bank_mask:0xf bound_ctrl:1
	ds_read_b128 v[18:21], v90 offset:1792
	ds_read_b128 v[22:25], v89 offset:5888
	v_add_f32_dpp v0, v0, v0 quad_perm:[2,3,0,1] row_mask:0xf bank_mask:0xf bound_ctrl:1
	ds_read_b128 v[34:37], v90 offset:5888
	ds_read_b128 v[38:41], v90 offset:9984
	v_add_f32_dpp v0, v0, v0 row_half_mirror row_mask:0xf bank_mask:0xf bound_ctrl:1
	ds_read_b128 v[42:45], v89 offset:18176
	s_nop 0
	v_add_f32_dpp v0, v0, v0 row_ror:8 row_mask:0xf bank_mask:0xf bound_ctrl:1
	s_waitcnt lgkmcnt(12)
	v_pk_fma_f32 v[46:47], v[46:47], v[0:1], v[62:63] op_sel_hi:[1,0,1] neg_lo:[1,0,0] neg_hi:[1,0,0]
	v_pk_fma_f32 v[10:11], v[48:49], v[0:1], v[10:11] op_sel_hi:[1,0,1] neg_lo:[1,0,0] neg_hi:[1,0,0]
	s_waitcnt lgkmcnt(7)
	v_pk_mul_f32 v[30:31], v[30:31], v[46:47]
	v_pk_mul_f32 v[48:49], v[52:53], v[10:11]
	v_pk_mul_f32 v[14:15], v[14:15], v[46:47]
	v_pk_mul_f32 v[16:17], v[16:17], v[10:11]
	v_pk_fma_f32 v[46:47], v[50:51], v[46:47], v[48:49]
	v_pk_fma_f32 v[10:11], v[32:33], v[10:11], v[30:31]
	v_add_f32_e32 v10, v10, v11
	v_add_f32_e32 v97, v46, v47
	v_pk_fma_f32 v[50:51], v[12:13], v[26:27], v[14:15] op_sel_hi:[0,1,1]
	v_add_f32_dpp v0, v10, v10 quad_perm:[1,0,3,2] row_mask:0xf bank_mask:0xf bound_ctrl:1
	v_pk_fma_f32 v[52:53], v[12:13], v[28:29], v[16:17] op_sel_hi:[0,1,1]
	ds_read_b128 v[10:13], v90 offset:2048
	v_add_f32_dpp v0, v0, v0 quad_perm:[2,3,0,1] row_mask:0xf bank_mask:0xf bound_ctrl:1
	ds_read_b128 v[14:17], v89 offset:6144
	ds_read_b128 v[26:29], v90 offset:6144
	v_add_f32_dpp v0, v0, v0 row_half_mirror row_mask:0xf bank_mask:0xf bound_ctrl:1
	ds_read_b128 v[30:33], v90 offset:10240
	ds_read_b128 v[46:49], v89 offset:18432
	v_add_f32_dpp v0, v0, v0 row_ror:8 row_mask:0xf bank_mask:0xf bound_ctrl:1
	s_waitcnt lgkmcnt(11)
	v_pk_fma_f32 v[50:51], v[54:55], v[0:1], v[50:51] op_sel_hi:[1,0,1] neg_lo:[1,0,0] neg_hi:[1,0,0]
	v_pk_fma_f32 v[52:53], v[56:57], v[0:1], v[52:53] op_sel_hi:[1,0,1] neg_lo:[1,0,0] neg_hi:[1,0,0]
	s_waitcnt lgkmcnt(7)
	v_pk_mul_f32 v[34:35], v[34:35], v[50:51]
	v_pk_mul_f32 v[54:55], v[60:61], v[52:53]
	v_pk_mul_f32 v[18:19], v[18:19], v[50:51]
	v_pk_fma_f32 v[50:51], v[58:59], v[50:51], v[54:55]
	v_pk_fma_f32 v[34:35], v[36:37], v[52:53], v[34:35]
	v_pk_fma_f32 v[58:59], v[82:83], v[22:23], v[18:19] op_sel_hi:[0,1,1]
	v_add_f32_e32 v18, v34, v35
	v_add_f32_e32 v98, v50, v51
	v_pk_mul_f32 v[20:21], v[20:21], v[52:53]
	v_add_f32_dpp v0, v18, v18 quad_perm:[1,0,3,2] row_mask:0xf bank_mask:0xf bound_ctrl:1
	v_pk_fma_f32 v[60:61], v[82:83], v[24:25], v[20:21] op_sel_hi:[0,1,1]
	ds_read_b128 v[18:21], v90 offset:2304
	v_add_f32_dpp v0, v0, v0 quad_perm:[2,3,0,1] row_mask:0xf bank_mask:0xf bound_ctrl:1
	ds_read_b128 v[22:25], v89 offset:6400
	ds_read_b128 v[34:37], v90 offset:6400
	v_add_f32_dpp v0, v0, v0 row_half_mirror row_mask:0xf bank_mask:0xf bound_ctrl:1
	ds_read_b128 v[50:53], v90 offset:10496
	ds_read_b128 v[54:57], v89 offset:18688
	v_add_f32_dpp v0, v0, v0 row_ror:8 row_mask:0xf bank_mask:0xf bound_ctrl:1
	s_waitcnt lgkmcnt(11)
	v_pk_fma_f32 v[38:39], v[38:39], v[0:1], v[58:59] op_sel_hi:[1,0,1] neg_lo:[1,0,0] neg_hi:[1,0,0]
	v_pk_fma_f32 v[40:41], v[40:41], v[0:1], v[60:61] op_sel_hi:[1,0,1] neg_lo:[1,0,0] neg_hi:[1,0,0]
	s_waitcnt lgkmcnt(7)
	v_pk_mul_f32 v[26:27], v[26:27], v[38:39]
	v_pk_mul_f32 v[44:45], v[44:45], v[40:41]
	v_pk_mul_f32 v[10:11], v[10:11], v[38:39]
	v_pk_fma_f32 v[38:39], v[42:43], v[38:39], v[44:45]
	v_pk_fma_f32 v[26:27], v[28:29], v[40:41], v[26:27]
	v_pk_fma_f32 v[58:59], v[6:7], v[14:15], v[10:11] op_sel_hi:[0,1,1]
	v_add_f32_e32 v99, v38, v39
	v_add_f32_e32 v10, v26, v27
	ds_write_b128 v91, v[96:99] offset:47104
	v_pk_mul_f32 v[12:13], v[12:13], v[40:41]
	v_add_f32_dpp v0, v10, v10 quad_perm:[1,0,3,2] row_mask:0xf bank_mask:0xf bound_ctrl:1
	v_pk_fma_f32 v[60:61], v[6:7], v[16:17], v[12:13] op_sel_hi:[0,1,1]
	ds_read_b128 v[10:13], v90 offset:2560
	v_add_f32_dpp v0, v0, v0 quad_perm:[2,3,0,1] row_mask:0xf bank_mask:0xf bound_ctrl:1
	ds_read_b128 v[14:17], v89 offset:6656
	ds_read_b128 v[26:29], v90 offset:6656
	v_add_f32_dpp v0, v0, v0 row_half_mirror row_mask:0xf bank_mask:0xf bound_ctrl:1
	ds_read_b128 v[38:41], v90 offset:10752
	ds_read_b128 v[42:45], v89 offset:18944
	v_add_f32_dpp v0, v0, v0 row_ror:8 row_mask:0xf bank_mask:0xf bound_ctrl:1
	s_waitcnt lgkmcnt(12)
	v_pk_fma_f32 v[30:31], v[30:31], v[0:1], v[58:59] op_sel_hi:[1,0,1] neg_lo:[1,0,0] neg_hi:[1,0,0]
	v_pk_fma_f32 v[32:33], v[32:33], v[0:1], v[60:61] op_sel_hi:[1,0,1] neg_lo:[1,0,0] neg_hi:[1,0,0]
	s_waitcnt lgkmcnt(8)
	v_pk_mul_f32 v[34:35], v[34:35], v[30:31]
	v_pk_mul_f32 v[48:49], v[48:49], v[32:33]
	v_pk_mul_f32 v[18:19], v[18:19], v[30:31]
	v_pk_mul_f32 v[20:21], v[20:21], v[32:33]
	v_pk_fma_f32 v[30:31], v[46:47], v[30:31], v[48:49]
	v_pk_fma_f32 v[32:33], v[36:37], v[32:33], v[34:35]
	v_pk_fma_f32 v[58:59], v[6:7], v[22:23], v[18:19] op_sel:[1,0,0]
	v_add_f32_e32 v18, v32, v33
	v_add_f32_e32 v92, v30, v31
	v_pk_fma_f32 v[6:7], v[6:7], v[24:25], v[20:21] op_sel:[1,0,0]
	v_add_f32_dpp v0, v18, v18 quad_perm:[1,0,3,2] row_mask:0xf bank_mask:0xf bound_ctrl:1
	ds_read_b128 v[18:21], v90 offset:2816
	ds_read_b128 v[22:25], v89 offset:6912
	v_add_f32_dpp v0, v0, v0 quad_perm:[2,3,0,1] row_mask:0xf bank_mask:0xf bound_ctrl:1
	ds_read_b128 v[30:33], v90 offset:6912
	ds_read_b128 v[34:37], v90 offset:11008
	v_add_f32_dpp v0, v0, v0 row_half_mirror row_mask:0xf bank_mask:0xf bound_ctrl:1
	ds_read_b128 v[46:49], v89 offset:19200
	s_nop 0
	v_add_f32_dpp v0, v0, v0 row_ror:8 row_mask:0xf bank_mask:0xf bound_ctrl:1
	s_waitcnt lgkmcnt(12)
	v_pk_fma_f32 v[50:51], v[50:51], v[0:1], v[58:59] op_sel_hi:[1,0,1] neg_lo:[1,0,0] neg_hi:[1,0,0]
	v_pk_fma_f32 v[6:7], v[52:53], v[0:1], v[6:7] op_sel_hi:[1,0,1] neg_lo:[1,0,0] neg_hi:[1,0,0]
	s_waitcnt lgkmcnt(7)
	v_pk_mul_f32 v[26:27], v[26:27], v[50:51]
	v_pk_mul_f32 v[52:53], v[56:57], v[6:7]
	v_pk_mul_f32 v[10:11], v[10:11], v[50:51]
	v_pk_mul_f32 v[12:13], v[12:13], v[6:7]
	v_pk_fma_f32 v[50:51], v[54:55], v[50:51], v[52:53]
	v_pk_fma_f32 v[6:7], v[28:29], v[6:7], v[26:27]
	v_add_f32_e32 v6, v6, v7
	v_add_f32_e32 v93, v50, v51
	v_pk_fma_f32 v[54:55], v[8:9], v[14:15], v[10:11] op_sel_hi:[0,1,1]
	v_add_f32_dpp v0, v6, v6 quad_perm:[1,0,3,2] row_mask:0xf bank_mask:0xf bound_ctrl:1
	v_pk_fma_f32 v[56:57], v[8:9], v[16:17], v[12:13] op_sel_hi:[0,1,1]
	ds_read_b128 v[6:9], v90 offset:3072
	v_add_f32_dpp v0, v0, v0 quad_perm:[2,3,0,1] row_mask:0xf bank_mask:0xf bound_ctrl:1
	ds_read_b128 v[10:13], v89 offset:7168
	ds_read_b128 v[14:17], v90 offset:7168
	v_add_f32_dpp v0, v0, v0 row_half_mirror row_mask:0xf bank_mask:0xf bound_ctrl:1
	ds_read_b128 v[26:29], v90 offset:11264
	ds_read_b128 v[50:53], v89 offset:19456
	v_add_f32_dpp v0, v0, v0 row_ror:8 row_mask:0xf bank_mask:0xf bound_ctrl:1
	s_waitcnt lgkmcnt(11)
	v_pk_fma_f32 v[38:39], v[38:39], v[0:1], v[54:55] op_sel_hi:[1,0,1] neg_lo:[1,0,0] neg_hi:[1,0,0]
	v_pk_fma_f32 v[40:41], v[40:41], v[0:1], v[56:57] op_sel_hi:[1,0,1] neg_lo:[1,0,0] neg_hi:[1,0,0]
	s_waitcnt lgkmcnt(7)
	v_pk_mul_f32 v[30:31], v[30:31], v[38:39]
	v_pk_mul_f32 v[44:45], v[44:45], v[40:41]
	v_pk_mul_f32 v[18:19], v[18:19], v[38:39]
	v_pk_fma_f32 v[38:39], v[42:43], v[38:39], v[44:45]
	v_pk_fma_f32 v[30:31], v[32:33], v[40:41], v[30:31]
	v_pk_fma_f32 v[54:55], v[84:85], v[22:23], v[18:19] op_sel_hi:[0,1,1]
	v_add_f32_e32 v18, v30, v31
	v_add_f32_e32 v94, v38, v39
	v_pk_mul_f32 v[20:21], v[20:21], v[40:41]
	v_add_f32_dpp v0, v18, v18 quad_perm:[1,0,3,2] row_mask:0xf bank_mask:0xf bound_ctrl:1
	v_pk_fma_f32 v[56:57], v[84:85], v[24:25], v[20:21] op_sel_hi:[0,1,1]
	ds_read_b128 v[18:21], v90 offset:3328
	v_add_f32_dpp v0, v0, v0 quad_perm:[2,3,0,1] row_mask:0xf bank_mask:0xf bound_ctrl:1
	ds_read_b128 v[22:25], v89 offset:7424
	ds_read_b128 v[30:33], v90 offset:7424
	v_add_f32_dpp v0, v0, v0 row_half_mirror row_mask:0xf bank_mask:0xf bound_ctrl:1
	ds_read_b128 v[38:41], v90 offset:11520
	ds_read_b128 v[42:45], v89 offset:19712
	v_add_f32_dpp v0, v0, v0 row_ror:8 row_mask:0xf bank_mask:0xf bound_ctrl:1
	s_waitcnt lgkmcnt(11)
	v_pk_fma_f32 v[34:35], v[34:35], v[0:1], v[54:55] op_sel_hi:[1,0,1] neg_lo:[1,0,0] neg_hi:[1,0,0]
	v_pk_fma_f32 v[36:37], v[36:37], v[0:1], v[56:57] op_sel_hi:[1,0,1] neg_lo:[1,0,0] neg_hi:[1,0,0]
	s_waitcnt lgkmcnt(7)
	v_pk_mul_f32 v[14:15], v[14:15], v[34:35]
	v_pk_mul_f32 v[48:49], v[48:49], v[36:37]
	v_pk_mul_f32 v[6:7], v[6:7], v[34:35]
	v_pk_fma_f32 v[34:35], v[46:47], v[34:35], v[48:49]
	v_pk_fma_f32 v[14:15], v[16:17], v[36:37], v[14:15]
	v_pk_fma_f32 v[54:55], v[2:3], v[10:11], v[6:7] op_sel_hi:[0,1,1]
	v_add_f32_e32 v95, v34, v35
	v_add_f32_e32 v6, v14, v15
	ds_write_b128 v91, v[92:95] offset:51200
	v_pk_mul_f32 v[8:9], v[8:9], v[36:37]
	v_add_f32_dpp v0, v6, v6 quad_perm:[1,0,3,2] row_mask:0xf bank_mask:0xf bound_ctrl:1
	v_pk_fma_f32 v[56:57], v[2:3], v[12:13], v[8:9] op_sel_hi:[0,1,1]
	ds_read_b128 v[6:9], v90 offset:3584
	v_add_f32_dpp v0, v0, v0 quad_perm:[2,3,0,1] row_mask:0xf bank_mask:0xf bound_ctrl:1
	ds_read_b128 v[10:13], v89 offset:7680
	ds_read_b128 v[14:17], v90 offset:7680
	v_add_f32_dpp v0, v0, v0 row_half_mirror row_mask:0xf bank_mask:0xf bound_ctrl:1
	ds_read_b128 v[34:37], v90 offset:11776
	ds_read_b128 v[46:49], v89 offset:19968
	v_add_f32_dpp v0, v0, v0 row_ror:8 row_mask:0xf bank_mask:0xf bound_ctrl:1
	s_waitcnt lgkmcnt(12)
	v_pk_fma_f32 v[26:27], v[26:27], v[0:1], v[54:55] op_sel_hi:[1,0,1] neg_lo:[1,0,0] neg_hi:[1,0,0]
	v_pk_fma_f32 v[28:29], v[28:29], v[0:1], v[56:57] op_sel_hi:[1,0,1] neg_lo:[1,0,0] neg_hi:[1,0,0]
	s_waitcnt lgkmcnt(8)
	v_pk_mul_f32 v[30:31], v[30:31], v[26:27]
	v_pk_mul_f32 v[52:53], v[52:53], v[28:29]
	v_pk_mul_f32 v[18:19], v[18:19], v[26:27]
	v_pk_mul_f32 v[20:21], v[20:21], v[28:29]
	v_pk_fma_f32 v[26:27], v[50:51], v[26:27], v[52:53]
	v_pk_fma_f32 v[28:29], v[32:33], v[28:29], v[30:31]
	v_pk_fma_f32 v[54:55], v[2:3], v[22:23], v[18:19] op_sel:[1,0,0]
	v_add_f32_e32 v18, v28, v29
	v_add_f32_e32 v96, v26, v27
	v_pk_fma_f32 v[2:3], v[2:3], v[24:25], v[20:21] op_sel:[1,0,0]
	v_add_f32_dpp v0, v18, v18 quad_perm:[1,0,3,2] row_mask:0xf bank_mask:0xf bound_ctrl:1
	ds_read_b128 v[18:21], v90 offset:3840
	ds_read_b128 v[22:25], v89 offset:7936
	v_add_f32_dpp v0, v0, v0 quad_perm:[2,3,0,1] row_mask:0xf bank_mask:0xf bound_ctrl:1
	ds_read_b128 v[26:29], v90 offset:7936
	ds_read_b128 v[30:33], v90 offset:12032
	v_add_f32_dpp v0, v0, v0 row_half_mirror row_mask:0xf bank_mask:0xf bound_ctrl:1
	ds_read_b128 v[50:53], v89 offset:20224
	s_nop 0
	v_add_f32_dpp v0, v0, v0 row_ror:8 row_mask:0xf bank_mask:0xf bound_ctrl:1
	s_waitcnt lgkmcnt(12)
	v_pk_fma_f32 v[38:39], v[38:39], v[0:1], v[54:55] op_sel_hi:[1,0,1] neg_lo:[1,0,0] neg_hi:[1,0,0]
	v_pk_fma_f32 v[2:3], v[40:41], v[0:1], v[2:3] op_sel_hi:[1,0,1] neg_lo:[1,0,0] neg_hi:[1,0,0]
	s_waitcnt lgkmcnt(7)
	v_pk_mul_f32 v[14:15], v[14:15], v[38:39]
	v_pk_mul_f32 v[40:41], v[44:45], v[2:3]
	v_pk_mul_f32 v[8:9], v[8:9], v[2:3]
	v_pk_fma_f32 v[2:3], v[16:17], v[2:3], v[14:15]
	v_pk_mul_f32 v[6:7], v[6:7], v[38:39]
	v_add_f32_e32 v0, v2, v3
	v_pk_fma_f32 v[6:7], v[4:5], v[10:11], v[6:7] op_sel_hi:[0,1,1]
	v_pk_fma_f32 v[4:5], v[4:5], v[12:13], v[8:9] op_sel_hi:[0,1,1]
	v_add_f32_dpp v0, v0, v0 quad_perm:[1,0,3,2] row_mask:0xf bank_mask:0xf bound_ctrl:1
	v_pk_fma_f32 v[38:39], v[42:43], v[38:39], v[40:41]
	ds_read_b128 v[108:111], v88 offset:4096
	v_add_f32_dpp v0, v0, v0 quad_perm:[2,3,0,1] row_mask:0xf bank_mask:0xf bound_ctrl:1
	v_add_f32_e32 v97, v38, v39
	ds_read_b128 v[100:103], v88
	v_add_f32_dpp v0, v0, v0 row_half_mirror row_mask:0xf bank_mask:0xf bound_ctrl:1
	ds_read_b128 v[120:123], v88 offset:8192
	ds_read_b128 v[112:115], v88 offset:4352
	v_add_f32_dpp v0, v0, v0 row_ror:8 row_mask:0xf bank_mask:0xf bound_ctrl:1
	s_waitcnt lgkmcnt(10)
	v_pk_fma_f32 v[2:3], v[34:35], v[0:1], v[6:7] op_sel_hi:[1,0,1] neg_lo:[1,0,0] neg_hi:[1,0,0]
	v_pk_fma_f32 v[4:5], v[36:37], v[0:1], v[4:5] op_sel_hi:[1,0,1] neg_lo:[1,0,0] neg_hi:[1,0,0]
	s_waitcnt lgkmcnt(6)
	v_pk_mul_f32 v[8:9], v[26:27], v[2:3]
	v_pk_mul_f32 v[6:7], v[48:49], v[4:5]
	v_pk_mul_f32 v[10:11], v[18:19], v[2:3]
	v_pk_mul_f32 v[12:13], v[20:21], v[4:5]
	v_pk_fma_f32 v[2:3], v[46:47], v[2:3], v[6:7]
	v_pk_fma_f32 v[4:5], v[28:29], v[4:5], v[8:9]
	v_add_f32_e32 v98, v2, v3
	v_add_f32_e32 v2, v4, v5
	v_pk_fma_f32 v[8:9], v[86:87], v[24:25], v[12:13] op_sel_hi:[0,1,1]
	s_nop 0
	v_add_f32_dpp v0, v2, v2 quad_perm:[1,0,3,2] row_mask:0xf bank_mask:0xf bound_ctrl:1
	v_pk_fma_f32 v[6:7], v[86:87], v[22:23], v[10:11] op_sel_hi:[0,1,1]
	ds_read_b128 v[104:107], v88 offset:256
	v_add_f32_dpp v0, v0, v0 quad_perm:[2,3,0,1] row_mask:0xf bank_mask:0xf bound_ctrl:1
	ds_read_b128 v[128:131], v88 offset:8448
	ds_read_b128 v[124:127], v88 offset:4608
	v_add_f32_dpp v0, v0, v0 row_half_mirror row_mask:0xf bank_mask:0xf bound_ctrl:1
	ds_read_b128 v[116:119], v88 offset:512
	s_nop 0
	v_add_f32_dpp v0, v0, v0 row_ror:8 row_mask:0xf bank_mask:0xf bound_ctrl:1
	s_waitcnt lgkmcnt(9)
	v_pk_fma_f32 v[76:77], v[32:33], v[0:1], v[8:9] op_sel_hi:[1,0,1] neg_lo:[1,0,0] neg_hi:[1,0,0]
	v_pk_fma_f32 v[74:75], v[30:31], v[0:1], v[6:7] op_sel_hi:[1,0,1] neg_lo:[1,0,0] neg_hi:[1,0,0]
	s_waitcnt lgkmcnt(8)
	v_pk_mul_f32 v[2:3], v[52:53], v[76:77]
	s_nop 0
	v_pk_fma_f32 v[2:3], v[50:51], v[74:75], v[2:3]
	s_nop 0
	v_add_f32_e32 v99, v2, v3
	ds_write_b128 v91, v[96:99] offset:55296
	v_lshlrev_b32_e32 v91, 2, v87
	v_add_u32_e32 v91, s97, v91
	v_add_u32_e32 v0, s2, v85
	v_add_u32_e32 v89, s2, v83
	v_add_u32_e32 v90, s3, v83
	v_add_u32_e32 v88, s96, v83
	s_cmpk_eq_i32 s26, 0x110
	s_waitcnt lgkmcnt(0)
	s_barrier
	s_cbranch_scc0 .LBB0_1050
	s_setprio 0
